# fill_rstd at the start of the in-/up-projection phases: the four per-unit blocks issue their partial-sum loads without waiting; sums, rsq and LDS stores run after one common wait (on top of v18)
# baseline (speedup 1.0000x reference)
.LBB0_168:
	s_or_b64 exec, exec, s[6:7]
	s_add_i32 s76, 0, 0x20000
	s_ashr_i32 s29, s24, 31
	s_ashr_i32 s3, s2, 31
	s_cmpk_lt_i32 s2, 0x100
	s_mov_b64 s[36:37], s[0:1]
	s_cselect_b64 s[20:21], -1, 0
	s_lshr_b32 s7, s3, 29
	s_waitcnt lgkmcnt(0)
	s_barrier
	s_mov_b64 s[84:85], 0
	s_mov_b64 s[86:87], 0
	s_mov_b64 s[88:89], 0
	s_mov_b64 s[90:91], 0
	s_load_dwordx2 s[34:35], s[36:37], 0xa0
	s_add_i32 s13, s2, s7
	s_and_b32 s7, s13, -8
	s_sub_i32 s75, s2, s7
	s_mov_b32 s12, s24
	s_mov_b32 s64, s2
	v_mov_b32_e32 v2, v224
	s_movk_i32 s6, 0xff
	s_cmp_lt_i32 s75, 0
	s_cselect_b64 s[30:31], -1, 0
	v_ashrrev_i32_e32 v4, 8, v2
	v_cmp_lt_u32_e32 vcc, s6, v2
	s_mov_b64 s[6:7], 0
	s_and_saveexec_b64 s[8:9], vcc
	s_xor_b64 s[8:9], exec, s[8:9]
	s_cbranch_execz .LBB0_172
	v_add_u32_e32 v3, -1, v4
	v_mov_b64_e32 v[0:1], s[2:3]
	v_mad_i64_i32 v[0:1], s[6:7], v3, s24, v[0:1]
	s_mov_b64 s[6:7], 0x180
	s_nop 0
	v_cmp_gt_i64_e32 vcc, s[6:7], v[0:1]
	s_mov_b64 s[6:7], 0
	s_and_saveexec_b64 s[10:11], vcc
	s_xor_b64 s[10:11], exec, s[10:11]
	s_cbranch_execz .LBB0_171
	v_ashrrev_i32_e32 v1, 31, v0
	v_lshrrev_b32_e32 v1, 29, v1
	v_add_u32_e32 v1, v0, v1
	v_ashrrev_i32_e32 v3, 3, v1
	v_and_b32_e32 v1, -8, v1
	v_sub_u32_e32 v0, v0, v1
	v_cmp_gt_i32_e32 vcc, 0, v0
	s_mov_b32 s14, 0x2aaaaaab
	s_mov_b64 s[6:7], exec
	v_cndmask_b32_e64 v1, 48, 49, vcc
	v_mul_lo_u32 v0, v1, v0
	v_add_u32_e32 v0, v0, v3
	v_mul_hi_i32 v1, v0, s14
	v_lshrrev_b32_e32 v3, 31, v1
	v_ashrrev_i32_e32 v1, 3, v1
	v_add_u32_e32 v1, v1, v3
	v_lshlrev_b32_e32 v3, 3, v1
	v_sub_u32_e32 v5, 64, v3
	v_min_i32_e32 v5, 8, v5
	v_sub_u32_e32 v6, 0, v5
	v_max_i32_e32 v5, v5, v6
	v_cvt_f32_u32_e32 v6, v5
	v_mul_lo_u32 v1, v1, 48
	v_sub_u32_e32 v0, v0, v1
	v_sub_u32_e32 v7, 0, v0
	v_rcp_iflag_f32_e32 v6, v6
	v_ashrrev_i32_e32 v1, 31, v0
	v_max_i32_e32 v0, v0, v7
	v_sub_u32_e32 v7, 0, v5
	v_mul_f32_e32 v6, 0x4f7ffffe, v6
	v_cvt_u32_f32_e32 v6, v6
	v_mul_lo_u32 v7, v7, v6
	v_mul_hi_u32 v7, v6, v7
	v_add_u32_e32 v6, v6, v7
	v_mul_hi_u32 v6, v0, v6
	v_mul_lo_u32 v6, v6, v5
	v_sub_u32_e32 v0, v0, v6
	v_sub_u32_e32 v6, v0, v5
	v_cmp_ge_u32_e32 vcc, v0, v5
	s_nop 1
	v_cndmask_b32_e32 v0, v0, v6, vcc
	v_sub_u32_e32 v6, v0, v5
	v_cmp_ge_u32_e32 vcc, v0, v5
	s_nop 1
	v_cndmask_b32_e32 v0, v0, v6, vcc
	v_xor_b32_e32 v0, v0, v1
	v_sub_u32_e32 v0, v0, v1
	v_add_u32_e32 v1, v0, v3

.LBB0_176:
	s_or_b64 exec, exec, s[8:9]
	v_lshl_add_u32 v3, v2, 2, s76
	s_and_saveexec_b64 s[8:9], s[6:7]
	s_cbranch_execz .LBB0_178
	v_lshl_or_b32 v0, v1, 8, v2
	v_min_i32_e32 v0, 0x3fff, v0
	v_cmp_lt_i32_e32 vcc, -1, v1
	s_nop 1
	v_cndmask_b32_e32 v0, 0, v0, vcc
	v_ashrrev_i32_e32 v1, 31, v0
	v_lshlrev_b64 v[0:1], 6, v[0:1]
	s_waitcnt lgkmcnt(0)
	v_lshl_add_u64 v[0:1], s[34:35], 0, v[0:1]
	s_mov_b64 s[84:85], exec
	global_load_dwordx4 v[160:163], v[0:1], off
	global_load_dwordx4 v[164:167], v[0:1], off offset:32
	global_load_dwordx4 v[168:171], v[0:1], off offset:16
	global_load_dwordx4 v[172:175], v[0:1], off offset:48
	v_lshl_add_u32 v226, v4, 10, v3

.LBB0_181:
	v_lshl_or_b32 v0, v1, 8, v2
	v_min_i32_e32 v0, 0x3fff, v0
	v_cmp_lt_i32_e32 vcc, -1, v1
	s_nop 1
	v_cndmask_b32_e32 v0, 0, v0, vcc
	v_ashrrev_i32_e32 v1, 31, v0
	v_lshlrev_b64 v[0:1], 6, v[0:1]
	s_waitcnt lgkmcnt(0)
	v_lshl_add_u64 v[0:1], s[34:35], 0, v[0:1]
	s_mov_b64 s[86:87], exec
	global_load_dwordx4 v[176:179], v[0:1], off
	global_load_dwordx4 v[180:183], v[0:1], off offset:32
	global_load_dwordx4 v[184:187], v[0:1], off offset:16
	global_load_dwordx4 v[188:191], v[0:1], off offset:48
	v_lshl_add_u32 v227, v5, 10, v3

.LBB0_185:
	v_lshl_or_b32 v0, v1, 8, v2
	v_min_i32_e32 v0, 0x3fff, v0
	v_cmp_lt_i32_e32 vcc, -1, v1
	s_nop 1
	v_cndmask_b32_e32 v0, 0, v0, vcc
	v_ashrrev_i32_e32 v1, 31, v0
	v_lshlrev_b64 v[0:1], 6, v[0:1]
	s_waitcnt lgkmcnt(0)
	v_lshl_add_u64 v[0:1], s[34:35], 0, v[0:1]
	s_mov_b64 s[88:89], exec
	global_load_dwordx4 v[192:195], v[0:1], off
	global_load_dwordx4 v[196:199], v[0:1], off offset:32
	global_load_dwordx4 v[200:203], v[0:1], off offset:16
	global_load_dwordx4 v[204:207], v[0:1], off offset:48
	v_lshl_add_u32 v228, v5, 10, v3

.LBB0_189:
	v_lshl_or_b32 v0, v1, 8, v2
	v_min_i32_e32 v0, 0x3fff, v0
	v_cmp_lt_i32_e32 vcc, -1, v1
	s_nop 1
	v_cndmask_b32_e32 v0, 0, v0, vcc
	v_ashrrev_i32_e32 v1, 31, v0
	v_lshlrev_b64 v[0:1], 6, v[0:1]
	s_waitcnt lgkmcnt(0)
	v_lshl_add_u64 v[0:1], s[34:35], 0, v[0:1]
	s_mov_b64 s[90:91], exec
	global_load_dwordx4 v[208:211], v[0:1], off
	global_load_dwordx4 v[212:215], v[0:1], off offset:32
	global_load_dwordx4 v[216:219], v[0:1], off offset:16
	global_load_dwordx4 v[220:223], v[0:1], off offset:48
	v_lshl_add_u32 v229, v5, 10, v3
.LBB0_190:
	s_or_b64 exec, exec, s[8:9]
	s_mov_b64 s[92:93], exec
	s_waitcnt vmcnt(0)
	s_mov_b64 exec, s[84:85]
	s_cbranch_execz .Lfr_2539_0
	v_mov_b32_e32 v0, v160
	v_mov_b32_e32 v1, v164
	v_mov_b32_e32 v164, v161
	v_mov_b32_e32 v160, v162
	v_mov_b32_e32 v161, v166
	v_mov_b32_e32 v166, v163
	v_mov_b32_e32 v162, v168
	v_mov_b32_e32 v163, v172
	v_mov_b32_e32 v172, v169
	v_mov_b32_e32 v168, v170
	v_mov_b32_e32 v169, v174
	v_mov_b32_e32 v174, v171
	v_pk_add_f32 v[0:1], v[0:1], v[164:165]
	v_pk_add_f32 v[160:161], v[160:161], v[166:167]
	v_pk_add_f32 v[162:163], v[162:163], v[172:173]
	v_pk_add_f32 v[164:165], v[168:169], v[174:175]
	v_pk_add_f32 v[0:1], v[0:1], v[160:161]
	v_pk_add_f32 v[160:161], v[162:163], v[164:165]
	s_nop 0
	v_pk_add_f32 v[0:1], v[0:1], v[160:161]
	s_nop 0
	v_add_f32_e32 v0, v0, v1
	v_mov_b32_e32 v1, 0x358637bd
	v_fmac_f32_e32 v1, 0x3a800000, v0
	v_rsq_f32_e32 v0, v1
	ds_write_b32 v226, v0
.Lfr_2539_0:
	s_mov_b64 exec, s[86:87]
	s_cbranch_execz .Lfr_2539_1
	v_mov_b32_e32 v0, v176
	v_mov_b32_e32 v1, v180
	v_mov_b32_e32 v180, v177
	v_mov_b32_e32 v176, v178
	v_mov_b32_e32 v177, v182
	v_mov_b32_e32 v182, v179
	v_mov_b32_e32 v178, v184
	v_mov_b32_e32 v179, v188
	v_mov_b32_e32 v188, v185
	v_mov_b32_e32 v184, v186
	v_mov_b32_e32 v185, v190
	v_mov_b32_e32 v190, v187
	v_pk_add_f32 v[0:1], v[0:1], v[180:181]
	v_pk_add_f32 v[176:177], v[176:177], v[182:183]
	v_pk_add_f32 v[178:179], v[178:179], v[188:189]
	v_pk_add_f32 v[180:181], v[184:185], v[190:191]
	v_pk_add_f32 v[0:1], v[0:1], v[176:177]
	v_pk_add_f32 v[176:177], v[178:179], v[180:181]
	s_nop 0
	v_pk_add_f32 v[0:1], v[0:1], v[176:177]
	s_nop 0
	v_add_f32_e32 v0, v0, v1
	v_mov_b32_e32 v1, 0x358637bd
	v_fmac_f32_e32 v1, 0x3a800000, v0
	v_rsq_f32_e32 v0, v1
	ds_write_b32 v227, v0
.Lfr_2539_1:
	s_mov_b64 exec, s[88:89]
	s_cbranch_execz .Lfr_2539_2
	v_mov_b32_e32 v0, v192
	v_mov_b32_e32 v1, v196
	v_mov_b32_e32 v196, v193
	v_mov_b32_e32 v192, v194
	v_mov_b32_e32 v193, v198
	v_mov_b32_e32 v198, v195
	v_mov_b32_e32 v194, v200
	v_mov_b32_e32 v195, v204
	v_mov_b32_e32 v204, v201
	v_mov_b32_e32 v200, v202
	v_mov_b32_e32 v201, v206
	v_mov_b32_e32 v206, v203
	v_pk_add_f32 v[0:1], v[0:1], v[196:197]
	v_pk_add_f32 v[192:193], v[192:193], v[198:199]
	v_pk_add_f32 v[194:195], v[194:195], v[204:205]
	v_pk_add_f32 v[196:197], v[200:201], v[206:207]
	v_pk_add_f32 v[0:1], v[0:1], v[192:193]
	v_pk_add_f32 v[192:193], v[194:195], v[196:197]
	s_nop 0
	v_pk_add_f32 v[0:1], v[0:1], v[192:193]
	s_nop 0
	v_add_f32_e32 v0, v0, v1
	v_mov_b32_e32 v1, 0x358637bd
	v_fmac_f32_e32 v1, 0x3a800000, v0
	v_rsq_f32_e32 v0, v1
	ds_write_b32 v228, v0
.Lfr_2539_2:
	s_mov_b64 exec, s[90:91]
	s_cbranch_execz .Lfr_2539_3
	v_mov_b32_e32 v0, v208
	v_mov_b32_e32 v1, v212
	v_mov_b32_e32 v212, v209
	v_mov_b32_e32 v208, v210
	v_mov_b32_e32 v209, v214
	v_mov_b32_e32 v214, v211
	v_mov_b32_e32 v210, v216
	v_mov_b32_e32 v211, v220
	v_mov_b32_e32 v220, v217
	v_mov_b32_e32 v216, v218
	v_mov_b32_e32 v217, v222
	v_mov_b32_e32 v222, v219
	v_pk_add_f32 v[0:1], v[0:1], v[212:213]
	v_pk_add_f32 v[208:209], v[208:209], v[214:215]
	v_pk_add_f32 v[210:211], v[210:211], v[220:221]
	v_pk_add_f32 v[212:213], v[216:217], v[222:223]
	v_pk_add_f32 v[0:1], v[0:1], v[208:209]
	v_pk_add_f32 v[208:209], v[210:211], v[212:213]
	s_nop 0
	v_pk_add_f32 v[0:1], v[0:1], v[208:209]
	s_nop 0
	v_add_f32_e32 v0, v0, v1
	v_mov_b32_e32 v1, 0x358637bd
	v_fmac_f32_e32 v1, 0x3a800000, v0
	v_rsq_f32_e32 v0, v1
	ds_write_b32 v229, v0
.Lfr_2539_3:
	s_mov_b64 exec, s[92:93]
	v_mov_b32_e32 v8, v224
	v_cndmask_b32_e64 v0, 0, 1, s[20:21]
	s_waitcnt lgkmcnt(0)
	s_barrier
	v_cmp_ne_u32_e64 s[6:7], 1, v0
	s_andn2_b64 vcc, exec, s[20:21]
	v_readfirstlane_b32 s8, v8
	s_cbranch_vccnz .LBB0_192
	s_and_b64 s[10:11], s[30:31], exec
	s_cselect_b32 s9, s74, s73
	s_add_i32 s9, s9, s72
	s_ashr_i32 s10, s9, 31
	s_lshr_b32 s10, s10, 27
	s_add_i32 s10, s9, s10
	s_ashr_i32 s11, s10, 5
	s_lshl_b32 s11, s11, 3
	s_sub_i32 s13, 64, s11
	s_min_i32 s13, s13, 8
	s_abs_i32 s14, s13
	v_cvt_f32_u32_e32 v0, s14
	s_sub_i32 s16, 0, s14
	s_andn2_b32 s10, s10, 31
	s_sub_i32 s9, s9, s10
	v_rcp_iflag_f32_e32 v0, v0
	s_abs_i32 s10, s9
	s_xor_b32 s15, s9, s13
	s_ashr_i32 s15, s15, 31
	v_mul_f32_e32 v0, 0x4f7ffffe, v0
	v_cvt_u32_f32_e32 v0, v0
	s_nop 0
	v_readfirstlane_b32 s17, v0
	s_mul_i32 s16, s16, s17
	s_mul_hi_u32 s16, s17, s16
	s_add_i32 s17, s17, s16
	s_mul_hi_u32 s16, s10, s17
	s_mul_i32 s17, s16, s14
	s_sub_i32 s10, s10, s17
	s_add_i32 s18, s16, 1
	s_sub_i32 s17, s10, s14
	s_cmp_ge_u32 s10, s14
	s_cselect_b32 s16, s18, s16
	s_cselect_b32 s10, s17, s10
	s_add_i32 s17, s16, 1
	s_cmp_ge_u32 s10, s14
	s_cselect_b32 s10, s17, s16
	s_xor_b32 s10, s10, s15
	s_sub_i32 s14, s10, s15
	s_mul_i32 s10, s14, s13
	s_sub_i32 s9, s9, s10
	s_add_i32 s10, s9, s11
	s_add_i32 s52, s14, 6

.LBB0_808:
	s_or_b64 exec, exec, s[8:9]
	s_mov_b64 s[38:39], s[0:1]
	s_waitcnt vmcnt(1) lgkmcnt(0)
	v_mov_b32_e32 v0, v224
	s_barrier
	s_mov_b64 s[84:85], 0
	s_mov_b64 s[86:87], 0
	s_mov_b64 s[88:89], 0
	s_mov_b64 s[90:91], 0
	s_load_dwordx2 s[36:37], s[38:39], 0xa0
	s_nop 0
	v_and_b32_e32 v1, 0xff, v0
	v_ashrrev_i32_e32 v4, 8, v0
	v_bfe_u32 v2, v0, 6, 2
	v_and_b32_e32 v0, 63, v0
	v_mad_u32_u24 v0, v2, 62, v0
	v_mov_b64_e32 v[2:3], s[2:3]
	v_mad_i64_i32 v[2:3], s[8:9], v4, s24, v[2:3]
	s_mov_b64 s[8:9], 0x5c2
	v_lshl_add_u32 v1, v1, 2, s76
	v_cmp_gt_i64_e32 vcc, s[8:9], v[2:3]
	s_and_saveexec_b64 s[8:9], vcc
	s_cbranch_execz .LBB0_814
	v_ashrrev_i32_e32 v3, 31, v2
	v_lshrrev_b32_e32 v3, 29, v3
	v_add_u32_e32 v5, v2, v3
	v_and_b32_e32 v3, -8, v5
	v_sub_u32_e32 v3, v2, v3
	v_cmp_lt_i32_e32 vcc, 1, v3
	s_and_saveexec_b64 s[10:11], vcc
	s_xor_b64 s[10:11], exec, s[10:11]
	s_movk_i32 s12, 0xb8
	v_mul_lo_u32 v2, v3, s12
	v_or_b32_e32 v2, 2, v2
	s_or_saveexec_b64 s[10:11], s[10:11]
	v_ashrrev_i32_e32 v5, 3, v5
	s_xor_b64 exec, exec, s[10:11]
	s_movk_i32 s12, 0xb9
	v_mul_lo_u32 v2, v3, s12
	s_or_b64 exec, exec, s[10:11]
	v_add_u32_e32 v2, v2, v5
	s_mov_b32 s10, 0x2e8ba2e9
	v_mul_hi_i32 v3, v2, s10
	v_lshrrev_b32_e32 v5, 31, v3
	v_ashrrev_i32_e32 v3, 5, v3
	v_add_u32_e32 v3, v3, v5
	v_lshlrev_b32_e32 v5, 3, v3
	v_sub_u32_e32 v6, 0x43, v5
	v_min_i32_e32 v6, 8, v6
	v_sub_u32_e32 v7, 0, v6
	v_max_i32_e32 v6, v6, v7
	v_cvt_f32_u32_e32 v7, v6
	s_movk_i32 s10, 0xb0
	v_mul_lo_u32 v3, v3, s10
	v_sub_u32_e32 v2, v2, v3
	v_rcp_iflag_f32_e32 v7, v7
	v_sub_u32_e32 v8, 0, v2
	v_ashrrev_i32_e32 v3, 31, v2
	v_max_i32_e32 v2, v2, v8
	v_mul_f32_e32 v7, 0x4f7ffffe, v7
	v_cvt_u32_f32_e32 v7, v7
	v_sub_u32_e32 v8, 0, v6
	s_movk_i32 s10, 0xf8
	v_mul_lo_u32 v8, v8, v7
	v_mul_hi_u32 v8, v7, v8
	v_add_u32_e32 v7, v7, v8
	v_mul_hi_u32 v7, v2, v7
	v_mul_lo_u32 v7, v7, v6
	v_sub_u32_e32 v2, v2, v7
	v_sub_u32_e32 v7, v2, v6
	v_cmp_ge_u32_e32 vcc, v2, v6
	s_nop 1
	v_cndmask_b32_e32 v2, v2, v7, vcc
	v_sub_u32_e32 v7, v2, v6
	v_cmp_ge_u32_e32 vcc, v2, v6
	s_nop 1
	v_cndmask_b32_e32 v2, v2, v7, vcc
	v_xor_b32_e32 v2, v2, v3
	v_sub_u32_e32 v2, v2, v3
	v_add_u32_e32 v2, v5, v2
	v_mad_u64_u32 v[2:3], s[10:11], v2, s10, v[0:1]
	v_mov_b32_e32 v3, 0x4001
	v_med3_i32 v2, v2, 2, v3
	v_add_u32_e32 v2, -2, v2
	v_mov_b32_e32 v3, 0
	v_lshlrev_b64 v[2:3], 6, v[2:3]
	s_waitcnt lgkmcnt(0)
	v_lshl_add_u64 v[2:3], s[36:37], 0, v[2:3]
	s_mov_b64 s[84:85], exec
	global_load_dwordx4 v[160:163], v[2:3], off
	global_load_dwordx4 v[164:167], v[2:3], off offset:32
	global_load_dwordx4 v[168:171], v[2:3], off offset:16
	global_load_dwordx4 v[172:175], v[2:3], off offset:48
	v_lshl_add_u32 v226, v4, 10, v1
.LBB0_814:
	s_or_b64 exec, exec, s[8:9]
	v_add_u32_e32 v5, 2, v4
	v_mov_b64_e32 v[2:3], s[2:3]
	v_mad_i64_i32 v[2:3], s[8:9], v5, s24, v[2:3]
	s_mov_b64 s[8:9], 0x5c2
	s_nop 0
	v_cmp_gt_i64_e32 vcc, s[8:9], v[2:3]
	s_and_saveexec_b64 s[8:9], vcc
	s_cbranch_execz .LBB0_820
	v_ashrrev_i32_e32 v3, 31, v2
	v_lshrrev_b32_e32 v3, 29, v3
	v_add_u32_e32 v6, v2, v3
	v_and_b32_e32 v3, -8, v6
	v_sub_u32_e32 v3, v2, v3
	v_cmp_lt_i32_e32 vcc, 1, v3
	s_and_saveexec_b64 s[10:11], vcc
	s_xor_b64 s[10:11], exec, s[10:11]
	s_movk_i32 s12, 0xb8
	v_mul_lo_u32 v2, v3, s12
	v_or_b32_e32 v2, 2, v2
	s_or_saveexec_b64 s[10:11], s[10:11]
	v_ashrrev_i32_e32 v6, 3, v6
	s_xor_b64 exec, exec, s[10:11]
	s_movk_i32 s12, 0xb9
	v_mul_lo_u32 v2, v3, s12
	s_or_b64 exec, exec, s[10:11]
	v_add_u32_e32 v2, v2, v6
	s_mov_b32 s10, 0x2e8ba2e9
	v_mul_hi_i32 v3, v2, s10
	v_lshrrev_b32_e32 v6, 31, v3
	v_ashrrev_i32_e32 v3, 5, v3
	v_add_u32_e32 v3, v3, v6
	v_lshlrev_b32_e32 v6, 3, v3
	v_sub_u32_e32 v7, 0x43, v6
	v_min_i32_e32 v7, 8, v7
	v_sub_u32_e32 v8, 0, v7
	v_max_i32_e32 v7, v7, v8
	v_cvt_f32_u32_e32 v8, v7
	s_movk_i32 s10, 0xb0
	v_mul_lo_u32 v3, v3, s10
	v_sub_u32_e32 v2, v2, v3
	v_rcp_iflag_f32_e32 v8, v8
	v_sub_u32_e32 v9, 0, v2
	v_ashrrev_i32_e32 v3, 31, v2
	v_max_i32_e32 v2, v2, v9
	v_mul_f32_e32 v8, 0x4f7ffffe, v8
	v_cvt_u32_f32_e32 v8, v8
	v_sub_u32_e32 v9, 0, v7
	s_movk_i32 s10, 0xf8
	v_mul_lo_u32 v9, v9, v8
	v_mul_hi_u32 v9, v8, v9
	v_add_u32_e32 v8, v8, v9
	v_mul_hi_u32 v8, v2, v8
	v_mul_lo_u32 v8, v8, v7
	v_sub_u32_e32 v2, v2, v8
	v_sub_u32_e32 v8, v2, v7
	v_cmp_ge_u32_e32 vcc, v2, v7
	s_nop 1
	v_cndmask_b32_e32 v2, v2, v8, vcc
	v_sub_u32_e32 v8, v2, v7
	v_cmp_ge_u32_e32 vcc, v2, v7
	s_nop 1
	v_cndmask_b32_e32 v2, v2, v8, vcc
	v_xor_b32_e32 v2, v2, v3
	v_sub_u32_e32 v2, v2, v3
	v_add_u32_e32 v2, v6, v2
	v_mad_u64_u32 v[2:3], s[10:11], v2, s10, v[0:1]
	v_mov_b32_e32 v3, 0x4001
	v_med3_i32 v2, v2, 2, v3
	v_add_u32_e32 v2, -2, v2
	v_mov_b32_e32 v3, 0
	v_lshlrev_b64 v[2:3], 6, v[2:3]
	s_waitcnt lgkmcnt(0)
	v_lshl_add_u64 v[2:3], s[36:37], 0, v[2:3]
	s_mov_b64 s[86:87], exec
	global_load_dwordx4 v[176:179], v[2:3], off
	global_load_dwordx4 v[180:183], v[2:3], off offset:32
	global_load_dwordx4 v[184:187], v[2:3], off offset:16
	global_load_dwordx4 v[188:191], v[2:3], off offset:48
	v_lshl_add_u32 v227, v5, 10, v1
.LBB0_820:
	s_or_b64 exec, exec, s[8:9]
	v_add_u32_e32 v5, 4, v4
	v_mov_b64_e32 v[2:3], s[2:3]
	v_mad_i64_i32 v[2:3], s[8:9], v5, s24, v[2:3]
	s_mov_b64 s[8:9], 0x5c2
	s_nop 0
	v_cmp_gt_i64_e32 vcc, s[8:9], v[2:3]
	s_and_saveexec_b64 s[8:9], vcc
	s_cbranch_execz .LBB0_826
	v_ashrrev_i32_e32 v3, 31, v2
	v_lshrrev_b32_e32 v3, 29, v3
	v_add_u32_e32 v6, v2, v3
	v_and_b32_e32 v3, -8, v6
	v_sub_u32_e32 v3, v2, v3
	v_cmp_lt_i32_e32 vcc, 1, v3
	s_and_saveexec_b64 s[10:11], vcc
	s_xor_b64 s[10:11], exec, s[10:11]
	s_movk_i32 s12, 0xb8
	v_mul_lo_u32 v2, v3, s12
	v_or_b32_e32 v2, 2, v2
	s_or_saveexec_b64 s[10:11], s[10:11]
	v_ashrrev_i32_e32 v6, 3, v6
	s_xor_b64 exec, exec, s[10:11]
	s_movk_i32 s12, 0xb9
	v_mul_lo_u32 v2, v3, s12
	s_or_b64 exec, exec, s[10:11]
	v_add_u32_e32 v2, v2, v6
	s_mov_b32 s10, 0x2e8ba2e9
	v_mul_hi_i32 v3, v2, s10
	v_lshrrev_b32_e32 v6, 31, v3
	v_ashrrev_i32_e32 v3, 5, v3
	v_add_u32_e32 v3, v3, v6
	v_lshlrev_b32_e32 v6, 3, v3
	v_sub_u32_e32 v7, 0x43, v6
	v_min_i32_e32 v7, 8, v7
	v_sub_u32_e32 v8, 0, v7
	v_max_i32_e32 v7, v7, v8
	v_cvt_f32_u32_e32 v8, v7
	s_movk_i32 s10, 0xb0
	v_mul_lo_u32 v3, v3, s10
	v_sub_u32_e32 v2, v2, v3
	v_rcp_iflag_f32_e32 v8, v8
	v_sub_u32_e32 v9, 0, v2
	v_ashrrev_i32_e32 v3, 31, v2
	v_max_i32_e32 v2, v2, v9
	v_mul_f32_e32 v8, 0x4f7ffffe, v8
	v_cvt_u32_f32_e32 v8, v8
	v_sub_u32_e32 v9, 0, v7
	s_movk_i32 s10, 0xf8
	v_mul_lo_u32 v9, v9, v8
	v_mul_hi_u32 v9, v8, v9
	v_add_u32_e32 v8, v8, v9
	v_mul_hi_u32 v8, v2, v8
	v_mul_lo_u32 v8, v8, v7
	v_sub_u32_e32 v2, v2, v8
	v_sub_u32_e32 v8, v2, v7
	v_cmp_ge_u32_e32 vcc, v2, v7
	s_nop 1
	v_cndmask_b32_e32 v2, v2, v8, vcc
	v_sub_u32_e32 v8, v2, v7
	v_cmp_ge_u32_e32 vcc, v2, v7
	s_nop 1
	v_cndmask_b32_e32 v2, v2, v8, vcc
	v_xor_b32_e32 v2, v2, v3
	v_sub_u32_e32 v2, v2, v3
	v_add_u32_e32 v2, v6, v2
	v_mad_u64_u32 v[2:3], s[10:11], v2, s10, v[0:1]
	v_mov_b32_e32 v3, 0x4001
	v_med3_i32 v2, v2, 2, v3
	v_add_u32_e32 v2, -2, v2
	v_mov_b32_e32 v3, 0
	v_lshlrev_b64 v[2:3], 6, v[2:3]
	s_waitcnt lgkmcnt(0)
	v_lshl_add_u64 v[2:3], s[36:37], 0, v[2:3]
	s_mov_b64 s[88:89], exec
	global_load_dwordx4 v[192:195], v[2:3], off
	global_load_dwordx4 v[196:199], v[2:3], off offset:32
	global_load_dwordx4 v[200:203], v[2:3], off offset:16
	global_load_dwordx4 v[204:207], v[2:3], off offset:48
	v_lshl_add_u32 v228, v5, 10, v1
.LBB0_826:
	s_or_b64 exec, exec, s[8:9]
	v_add_u32_e32 v4, 6, v4
	v_mov_b64_e32 v[2:3], s[2:3]
	v_mad_i64_i32 v[2:3], s[8:9], v4, s24, v[2:3]
	s_mov_b64 s[8:9], 0x5c2
	s_nop 0
	v_cmp_gt_i64_e32 vcc, s[8:9], v[2:3]
	s_and_saveexec_b64 s[8:9], vcc
	s_cbranch_execz .LBB0_832
	v_ashrrev_i32_e32 v3, 31, v2
	v_lshrrev_b32_e32 v3, 29, v3
	v_add_u32_e32 v5, v2, v3
	v_and_b32_e32 v3, -8, v5
	v_sub_u32_e32 v3, v2, v3
	v_cmp_lt_i32_e32 vcc, 1, v3
	s_and_saveexec_b64 s[10:11], vcc
	s_xor_b64 s[10:11], exec, s[10:11]
	s_movk_i32 s12, 0xb8
	v_mul_lo_u32 v2, v3, s12
	v_or_b32_e32 v2, 2, v2
	s_or_saveexec_b64 s[10:11], s[10:11]
	v_ashrrev_i32_e32 v5, 3, v5
	s_xor_b64 exec, exec, s[10:11]
	s_movk_i32 s12, 0xb9
	v_mul_lo_u32 v2, v3, s12
	s_or_b64 exec, exec, s[10:11]
	v_add_u32_e32 v2, v2, v5
	s_mov_b32 s10, 0x2e8ba2e9
	v_mul_hi_i32 v3, v2, s10
	v_lshrrev_b32_e32 v5, 31, v3
	v_ashrrev_i32_e32 v3, 5, v3
	v_add_u32_e32 v3, v3, v5
	v_lshlrev_b32_e32 v5, 3, v3
	v_sub_u32_e32 v6, 0x43, v5
	v_min_i32_e32 v6, 8, v6
	v_sub_u32_e32 v7, 0, v6
	v_max_i32_e32 v6, v6, v7
	v_cvt_f32_u32_e32 v7, v6
	s_movk_i32 s10, 0xb0
	v_mul_lo_u32 v3, v3, s10
	v_sub_u32_e32 v2, v2, v3
	v_rcp_iflag_f32_e32 v7, v7
	v_sub_u32_e32 v8, 0, v2
	v_ashrrev_i32_e32 v3, 31, v2
	v_max_i32_e32 v2, v2, v8
	v_mul_f32_e32 v7, 0x4f7ffffe, v7
	v_cvt_u32_f32_e32 v7, v7
	v_sub_u32_e32 v8, 0, v6
	s_movk_i32 s10, 0xf8
	v_mul_lo_u32 v8, v8, v7
	v_mul_hi_u32 v8, v7, v8
	v_add_u32_e32 v7, v7, v8
	v_mul_hi_u32 v7, v2, v7
	v_mul_lo_u32 v7, v7, v6
	v_sub_u32_e32 v2, v2, v7
	v_sub_u32_e32 v7, v2, v6
	v_cmp_ge_u32_e32 vcc, v2, v6
	s_nop 1
	v_cndmask_b32_e32 v2, v2, v7, vcc
	v_sub_u32_e32 v7, v2, v6
	v_cmp_ge_u32_e32 vcc, v2, v6
	s_nop 1
	v_cndmask_b32_e32 v2, v2, v7, vcc
	v_xor_b32_e32 v2, v2, v3
	v_sub_u32_e32 v2, v2, v3
	v_add_u32_e32 v2, v5, v2
	v_mad_u64_u32 v[2:3], s[10:11], v2, s10, v[0:1]
	v_mov_b32_e32 v0, 0x4001
	v_med3_i32 v0, v2, 2, v0
	v_add_u32_e32 v2, -2, v0
	v_mov_b32_e32 v3, 0
	v_lshlrev_b64 v[2:3], 6, v[2:3]
	s_waitcnt lgkmcnt(0)
	v_lshl_add_u64 v[2:3], s[36:37], 0, v[2:3]
	s_mov_b64 s[90:91], exec
	global_load_dwordx4 v[208:211], v[2:3], off
	global_load_dwordx4 v[212:215], v[2:3], off offset:32
	global_load_dwordx4 v[216:219], v[2:3], off offset:16
	global_load_dwordx4 v[220:223], v[2:3], off offset:48
	v_lshl_add_u32 v229, v4, 10, v1
.LBB0_832:
	s_or_b64 exec, exec, s[8:9]
	s_mov_b64 s[92:93], exec
	s_waitcnt vmcnt(0)
	s_mov_b64 exec, s[84:85]
	s_cbranch_execz .Lfr_22147_0
	v_mov_b32_e32 v2, v160
	v_mov_b32_e32 v3, v164
	v_mov_b32_e32 v164, v161
	v_mov_b32_e32 v160, v162
	v_mov_b32_e32 v161, v166
	v_mov_b32_e32 v166, v163
	v_mov_b32_e32 v162, v168
	v_mov_b32_e32 v163, v172
	v_mov_b32_e32 v172, v169
	v_mov_b32_e32 v168, v170
	v_mov_b32_e32 v169, v174
	v_mov_b32_e32 v174, v171
	v_pk_add_f32 v[2:3], v[2:3], v[164:165]
	v_pk_add_f32 v[160:161], v[160:161], v[166:167]
	v_pk_add_f32 v[162:163], v[162:163], v[172:173]
	v_pk_add_f32 v[164:165], v[168:169], v[174:175]
	v_pk_add_f32 v[2:3], v[2:3], v[160:161]
	v_pk_add_f32 v[160:161], v[162:163], v[164:165]
	s_nop 0
	v_pk_add_f32 v[2:3], v[2:3], v[160:161]
	s_nop 0
	v_add_f32_e32 v2, v2, v3
	v_mov_b32_e32 v3, 0x358637bd
	v_fmac_f32_e32 v3, 0x3a800000, v2
	v_rsq_f32_e32 v2, v3
	ds_write_b32 v226, v2
.Lfr_22147_0:
	s_mov_b64 exec, s[86:87]
	s_cbranch_execz .Lfr_22147_1
	v_mov_b32_e32 v2, v176
	v_mov_b32_e32 v3, v180
	v_mov_b32_e32 v180, v177
	v_mov_b32_e32 v176, v178
	v_mov_b32_e32 v177, v182
	v_mov_b32_e32 v182, v179
	v_mov_b32_e32 v178, v184
	v_mov_b32_e32 v179, v188
	v_mov_b32_e32 v188, v185
	v_mov_b32_e32 v184, v186
	v_mov_b32_e32 v185, v190
	v_mov_b32_e32 v190, v187
	v_pk_add_f32 v[2:3], v[2:3], v[180:181]
	v_pk_add_f32 v[176:177], v[176:177], v[182:183]
	v_pk_add_f32 v[178:179], v[178:179], v[188:189]
	v_pk_add_f32 v[180:181], v[184:185], v[190:191]
	v_pk_add_f32 v[2:3], v[2:3], v[176:177]
	v_pk_add_f32 v[176:177], v[178:179], v[180:181]
	s_nop 0
	v_pk_add_f32 v[2:3], v[2:3], v[176:177]
	s_nop 0
	v_add_f32_e32 v2, v2, v3
	v_mov_b32_e32 v3, 0x358637bd
	v_fmac_f32_e32 v3, 0x3a800000, v2
	v_rsq_f32_e32 v2, v3
	ds_write_b32 v227, v2
.Lfr_22147_1:
	s_mov_b64 exec, s[88:89]
	s_cbranch_execz .Lfr_22147_2
	v_mov_b32_e32 v2, v192
	v_mov_b32_e32 v3, v196
	v_mov_b32_e32 v196, v193
	v_mov_b32_e32 v192, v194
	v_mov_b32_e32 v193, v198
	v_mov_b32_e32 v198, v195
	v_mov_b32_e32 v194, v200
	v_mov_b32_e32 v195, v204
	v_mov_b32_e32 v204, v201
	v_mov_b32_e32 v200, v202
	v_mov_b32_e32 v201, v206
	v_mov_b32_e32 v206, v203
	v_pk_add_f32 v[2:3], v[2:3], v[196:197]
	v_pk_add_f32 v[192:193], v[192:193], v[198:199]
	v_pk_add_f32 v[194:195], v[194:195], v[204:205]
	v_pk_add_f32 v[196:197], v[200:201], v[206:207]
	v_pk_add_f32 v[2:3], v[2:3], v[192:193]
	v_pk_add_f32 v[192:193], v[194:195], v[196:197]
	s_nop 0
	v_pk_add_f32 v[2:3], v[2:3], v[192:193]
	s_nop 0
	v_add_f32_e32 v2, v2, v3
	v_mov_b32_e32 v3, 0x358637bd
	v_fmac_f32_e32 v3, 0x3a800000, v2
	v_rsq_f32_e32 v2, v3
	ds_write_b32 v228, v2
.Lfr_22147_2:
	s_mov_b64 exec, s[90:91]
	s_cbranch_execz .Lfr_22147_3
	v_mov_b32_e32 v2, v208
	v_mov_b32_e32 v3, v212
	v_mov_b32_e32 v212, v209
	v_mov_b32_e32 v208, v210
	v_mov_b32_e32 v209, v214
	v_mov_b32_e32 v214, v211
	v_mov_b32_e32 v210, v216
	v_mov_b32_e32 v211, v220
	v_mov_b32_e32 v220, v217
	v_mov_b32_e32 v216, v218
	v_mov_b32_e32 v217, v222
	v_mov_b32_e32 v222, v219
	v_pk_add_f32 v[2:3], v[2:3], v[212:213]
	v_pk_add_f32 v[208:209], v[208:209], v[214:215]
	v_pk_add_f32 v[210:211], v[210:211], v[220:221]
	v_pk_add_f32 v[212:213], v[216:217], v[222:223]
	v_pk_add_f32 v[2:3], v[2:3], v[208:209]
	v_pk_add_f32 v[208:209], v[210:211], v[212:213]
	s_nop 0
	v_pk_add_f32 v[2:3], v[2:3], v[208:209]
	s_nop 0
	v_add_f32_e32 v0, v2, v3
	v_mov_b32_e32 v2, 0x358637bd
	v_fmac_f32_e32 v2, 0x3a800000, v0
	v_rsq_f32_e32 v0, v2
	ds_write_b32 v229, v0
.Lfr_22147_3:
	s_mov_b64 exec, s[92:93]
	s_cmpk_lt_i32 s2, 0x5c2
	v_mov_b32_e32 v8, v224
	s_waitcnt lgkmcnt(0)
	s_barrier
	s_cselect_b64 s[34:35], -1, 0
	s_cmpk_gt_i32 s2, 0x5c1
	s_mul_i32 s80, s75, 0xb9
	v_readfirstlane_b32 s10, v8
	s_mul_i32 s97, s75, 0xb8
	s_cbranch_scc1 .LBB0_834
	s_or_b32 s8, s97, 2
	s_cmp_lt_i32 s75, 2
	s_cselect_b32 s8, s80, s8
	s_add_i32 s8, s8, s72
	s_mul_hi_i32 s9, s8, 0x2e8ba2e9
	s_lshr_b32 s11, s9, 31
	s_ashr_i32 s9, s9, 5
	s_add_i32 s9, s9, s11
	s_lshl_b32 s11, s9, 3
	s_sub_i32 s12, 0x43, s11
	s_min_i32 s12, s12, 8
	s_abs_i32 s13, s12
	v_cvt_f32_u32_e32 v0, s13
	s_sub_i32 s15, 0, s13
	s_mulk_i32 s9, 0xb0
	s_sub_i32 s8, s8, s9
	v_rcp_iflag_f32_e32 v0, v0
	s_abs_i32 s9, s8
	s_xor_b32 s14, s8, s12
	s_ashr_i32 s14, s14, 31
	v_mul_f32_e32 v0, 0x4f7ffffe, v0
	v_cvt_u32_f32_e32 v0, v0
	s_nop 0
	v_readfirstlane_b32 s16, v0
	s_mul_i32 s15, s15, s16
	s_mul_hi_u32 s15, s16, s15
	s_add_i32 s16, s16, s15
	s_mul_hi_u32 s15, s9, s16
	s_mul_i32 s16, s15, s13
	s_sub_i32 s9, s9, s16
	s_add_i32 s17, s15, 1
	s_sub_i32 s16, s9, s13
	s_cmp_ge_u32 s9, s13
	s_cselect_b32 s15, s17, s15
	s_cselect_b32 s9, s16, s9
	s_add_i32 s16, s15, 1
	s_cmp_ge_u32 s9, s13
	s_cselect_b32 s9, s16, s15
	s_xor_b32 s9, s9, s14
	s_sub_i32 s14, s9, s14
	s_mul_i32 s9, s14, s12
	s_sub_i32 s8, s8, s9
	s_add_i32 s26, s8, s11

.LBB0_1134:
	s_or_b64 exec, exec, s[10:11]
	s_mov_b64 s[38:39], s[0:1]
	s_waitcnt lgkmcnt(0)
	s_barrier
	s_mov_b64 s[84:85], 0
	s_mov_b64 s[86:87], 0
	s_mov_b64 s[88:89], 0
	s_mov_b64 s[90:91], 0
	s_load_dwordx2 s[36:37], s[38:39], 0xa0
	s_mov_b32 s16, s24
	s_mov_b32 s64, s2
	v_mov_b32_e32 v2, v224
	s_movk_i32 s10, 0xff
	s_nop 0
	v_ashrrev_i32_e32 v4, 8, v2
	v_cmp_lt_u32_e32 vcc, s10, v2
	s_mov_b64 s[10:11], 0
	s_and_saveexec_b64 s[12:13], vcc
	s_xor_b64 s[12:13], exec, s[12:13]
	s_cbranch_execnz .LBB0_1236
	s_or_saveexec_b64 s[12:13], s[12:13]
	v_and_b32_e32 v2, 0xff, v2
	s_xor_b64 exec, exec, s[12:13]
	s_cbranch_execnz .LBB0_1239

.LBB0_1137:
	v_lshl_or_b32 v0, v1, 8, v2
	v_min_i32_e32 v0, 0x3fff, v0
	v_cmp_lt_i32_e32 vcc, -1, v1
	s_nop 1
	v_cndmask_b32_e32 v0, 0, v0, vcc
	v_ashrrev_i32_e32 v1, 31, v0
	v_lshlrev_b64 v[0:1], 6, v[0:1]
	s_waitcnt lgkmcnt(0)
	v_lshl_add_u64 v[0:1], s[36:37], 0, v[0:1]
	s_mov_b64 s[84:85], exec
	global_load_dwordx4 v[160:163], v[0:1], off
	global_load_dwordx4 v[164:167], v[0:1], off offset:32
	global_load_dwordx4 v[168:171], v[0:1], off offset:16
	global_load_dwordx4 v[172:175], v[0:1], off offset:48
	v_lshl_add_u32 v226, v4, 10, v3

.LBB0_1141:
	v_lshl_or_b32 v0, v1, 8, v2
	v_min_i32_e32 v0, 0x3fff, v0
	v_cmp_lt_i32_e32 vcc, -1, v1
	s_nop 1
	v_cndmask_b32_e32 v0, 0, v0, vcc
	v_ashrrev_i32_e32 v1, 31, v0
	v_lshlrev_b64 v[0:1], 6, v[0:1]
	s_waitcnt lgkmcnt(0)
	v_lshl_add_u64 v[0:1], s[36:37], 0, v[0:1]
	s_mov_b64 s[86:87], exec
	global_load_dwordx4 v[176:179], v[0:1], off
	global_load_dwordx4 v[180:183], v[0:1], off offset:32
	global_load_dwordx4 v[184:187], v[0:1], off offset:16
	global_load_dwordx4 v[188:191], v[0:1], off offset:48
	v_lshl_add_u32 v227, v5, 10, v3

.LBB0_1145:
	v_lshl_or_b32 v0, v1, 8, v2
	v_min_i32_e32 v0, 0x3fff, v0
	v_cmp_lt_i32_e32 vcc, -1, v1
	s_nop 1
	v_cndmask_b32_e32 v0, 0, v0, vcc
	v_ashrrev_i32_e32 v1, 31, v0
	v_lshlrev_b64 v[0:1], 6, v[0:1]
	s_waitcnt lgkmcnt(0)
	v_lshl_add_u64 v[0:1], s[36:37], 0, v[0:1]
	s_mov_b64 s[88:89], exec
	global_load_dwordx4 v[192:195], v[0:1], off
	global_load_dwordx4 v[196:199], v[0:1], off offset:32
	global_load_dwordx4 v[200:203], v[0:1], off offset:16
	global_load_dwordx4 v[204:207], v[0:1], off offset:48
	v_lshl_add_u32 v228, v5, 10, v3

.LBB0_1149:
	v_lshl_or_b32 v0, v1, 8, v2
	v_min_i32_e32 v0, 0x3fff, v0
	v_cmp_lt_i32_e32 vcc, -1, v1
	s_nop 1
	v_cndmask_b32_e32 v0, 0, v0, vcc
	v_ashrrev_i32_e32 v1, 31, v0
	v_lshlrev_b64 v[0:1], 6, v[0:1]
	s_waitcnt lgkmcnt(0)
	v_lshl_add_u64 v[0:1], s[36:37], 0, v[0:1]
	s_mov_b64 s[90:91], exec
	global_load_dwordx4 v[208:211], v[0:1], off
	global_load_dwordx4 v[212:215], v[0:1], off offset:32
	global_load_dwordx4 v[216:219], v[0:1], off offset:16
	global_load_dwordx4 v[220:223], v[0:1], off offset:48
	v_lshl_add_u32 v229, v5, 10, v3
.LBB0_1150:
	s_or_b64 exec, exec, s[12:13]
	s_mov_b64 s[92:93], exec
	s_waitcnt vmcnt(0)
	s_mov_b64 exec, s[84:85]
	s_cbranch_execz .Lfr_30698_0
	v_mov_b32_e32 v0, v160
	v_mov_b32_e32 v1, v164
	v_mov_b32_e32 v164, v161
	v_mov_b32_e32 v160, v162
	v_mov_b32_e32 v161, v166
	v_mov_b32_e32 v166, v163
	v_mov_b32_e32 v162, v168
	v_mov_b32_e32 v163, v172
	v_mov_b32_e32 v172, v169
	v_mov_b32_e32 v168, v170
	v_mov_b32_e32 v169, v174
	v_mov_b32_e32 v174, v171
	v_pk_add_f32 v[0:1], v[0:1], v[164:165]
	v_pk_add_f32 v[160:161], v[160:161], v[166:167]
	v_pk_add_f32 v[162:163], v[162:163], v[172:173]
	v_pk_add_f32 v[164:165], v[168:169], v[174:175]
	v_pk_add_f32 v[0:1], v[0:1], v[160:161]
	v_pk_add_f32 v[160:161], v[162:163], v[164:165]
	s_nop 0
	v_pk_add_f32 v[0:1], v[0:1], v[160:161]
	s_nop 0
	v_add_f32_e32 v0, v0, v1
	v_mov_b32_e32 v1, 0x358637bd
	v_fmac_f32_e32 v1, 0x3a800000, v0
	v_rsq_f32_e32 v0, v1
	ds_write_b32 v226, v0

.Lfr_30698_3:
	s_mov_b64 exec, s[92:93]
	v_mov_b32_e32 v8, v224
	s_waitcnt lgkmcnt(0)
	s_barrier
	s_and_b64 vcc, exec, s[6:7]
	v_readfirstlane_b32 s10, v8
	s_cbranch_vccnz .LBB0_1152
	s_and_b64 s[12:13], s[30:31], exec
	s_cselect_b32 s11, s74, s73
	s_add_i32 s11, s11, s72
	s_ashr_i32 s12, s11, 31
	s_lshr_b32 s12, s12, 27
	s_add_i32 s12, s11, s12
	s_ashr_i32 s13, s12, 5
	s_lshl_b32 s13, s13, 3
	s_sub_i32 s14, 64, s13
	s_min_i32 s14, s14, 8
	s_abs_i32 s15, s14
	v_cvt_f32_u32_e32 v0, s15
	s_sub_i32 s18, 0, s15
	s_andn2_b32 s12, s12, 31
	s_sub_i32 s11, s11, s12
	v_rcp_iflag_f32_e32 v0, v0
	s_abs_i32 s12, s11
	s_xor_b32 s17, s11, s14
	s_ashr_i32 s17, s17, 31
	v_mul_f32_e32 v0, 0x4f7ffffe, v0
	v_cvt_u32_f32_e32 v0, v0
	s_nop 0
	v_readfirstlane_b32 s19, v0
	s_mul_i32 s18, s18, s19
	s_mul_hi_u32 s18, s19, s18
	s_add_i32 s19, s19, s18
	s_mul_hi_u32 s18, s12, s19
	s_mul_i32 s19, s18, s15
	s_sub_i32 s12, s12, s19
	s_add_i32 s20, s18, 1
	s_sub_i32 s19, s12, s15
	s_cmp_ge_u32 s12, s15
	s_cselect_b32 s18, s20, s18
	s_cselect_b32 s12, s19, s12
	s_add_i32 s19, s18, 1
	s_cmp_ge_u32 s12, s15
	s_cselect_b32 s12, s19, s18
	s_xor_b32 s12, s12, s17
	s_sub_i32 s15, s12, s17
	s_mul_i32 s12, s15, s14
	s_sub_i32 s11, s11, s12
	s_add_i32 s12, s11, s13
	s_add_i32 s56, s15, 6

.LBB0_1678:
	s_or_b64 exec, exec, s[10:11]
	s_mov_b64 s[14:15], s[0:1]
	s_waitcnt vmcnt(1) lgkmcnt(0)
	v_mov_b32_e32 v0, v224
	s_barrier
	s_mov_b64 s[84:85], 0
	s_mov_b64 s[86:87], 0
	s_mov_b64 s[88:89], 0
	s_mov_b64 s[90:91], 0
	s_load_dwordx2 s[16:17], s[14:15], 0xa0
	s_nop 0
	v_and_b32_e32 v1, 0xff, v0
	v_ashrrev_i32_e32 v4, 8, v0
	v_bfe_u32 v2, v0, 6, 2
	v_and_b32_e32 v0, 63, v0
	v_mad_u32_u24 v0, v2, 62, v0
	v_mov_b64_e32 v[2:3], s[2:3]
	v_mad_i64_i32 v[2:3], s[10:11], v4, s24, v[2:3]
	s_mov_b64 s[10:11], 0x5c2
	v_lshl_add_u32 v1, v1, 2, s76
	v_cmp_gt_i64_e32 vcc, s[10:11], v[2:3]
	s_and_saveexec_b64 s[10:11], vcc
	s_cbranch_execz .LBB0_1684
	v_ashrrev_i32_e32 v3, 31, v2
	v_lshrrev_b32_e32 v3, 29, v3
	v_add_u32_e32 v5, v2, v3
	v_and_b32_e32 v3, -8, v5
	v_sub_u32_e32 v3, v2, v3
	v_cmp_lt_i32_e32 vcc, 1, v3
	s_and_saveexec_b64 s[12:13], vcc
	s_xor_b64 s[12:13], exec, s[12:13]
	s_movk_i32 s18, 0xb8
	v_mul_lo_u32 v2, v3, s18
	v_or_b32_e32 v2, 2, v2
	s_or_saveexec_b64 s[12:13], s[12:13]
	v_ashrrev_i32_e32 v5, 3, v5
	s_xor_b64 exec, exec, s[12:13]
	s_movk_i32 s18, 0xb9
	v_mul_lo_u32 v2, v3, s18
	s_or_b64 exec, exec, s[12:13]
	v_add_u32_e32 v2, v2, v5
	s_mov_b32 s12, 0x2e8ba2e9
	v_mul_hi_i32 v3, v2, s12
	v_lshrrev_b32_e32 v5, 31, v3
	v_ashrrev_i32_e32 v3, 5, v3
	v_add_u32_e32 v3, v3, v5
	v_lshlrev_b32_e32 v5, 3, v3
	v_sub_u32_e32 v6, 0x43, v5
	v_min_i32_e32 v6, 8, v6
	v_sub_u32_e32 v7, 0, v6
	v_max_i32_e32 v6, v6, v7
	v_cvt_f32_u32_e32 v7, v6
	s_movk_i32 s12, 0xb0
	v_mul_lo_u32 v3, v3, s12
	v_sub_u32_e32 v2, v2, v3
	v_rcp_iflag_f32_e32 v7, v7
	v_sub_u32_e32 v8, 0, v2
	v_ashrrev_i32_e32 v3, 31, v2
	v_max_i32_e32 v2, v2, v8
	v_mul_f32_e32 v7, 0x4f7ffffe, v7
	v_cvt_u32_f32_e32 v7, v7
	v_sub_u32_e32 v8, 0, v6
	s_movk_i32 s12, 0xf8
	v_mul_lo_u32 v8, v8, v7
	v_mul_hi_u32 v8, v7, v8
	v_add_u32_e32 v7, v7, v8
	v_mul_hi_u32 v7, v2, v7
	v_mul_lo_u32 v7, v7, v6
	v_sub_u32_e32 v2, v2, v7
	v_sub_u32_e32 v7, v2, v6
	v_cmp_ge_u32_e32 vcc, v2, v6
	s_nop 1
	v_cndmask_b32_e32 v2, v2, v7, vcc
	v_sub_u32_e32 v7, v2, v6
	v_cmp_ge_u32_e32 vcc, v2, v6
	s_nop 1
	v_cndmask_b32_e32 v2, v2, v7, vcc
	v_xor_b32_e32 v2, v2, v3
	v_sub_u32_e32 v2, v2, v3
	v_add_u32_e32 v2, v5, v2
	v_mad_u64_u32 v[2:3], s[12:13], v2, s12, v[0:1]
	v_mov_b32_e32 v3, 0x4001
	v_med3_i32 v2, v2, 2, v3
	v_add_u32_e32 v2, -2, v2
	v_mov_b32_e32 v3, 0
	v_lshlrev_b64 v[2:3], 6, v[2:3]
	s_waitcnt lgkmcnt(0)
	v_lshl_add_u64 v[2:3], s[16:17], 0, v[2:3]
	s_mov_b64 s[84:85], exec
	global_load_dwordx4 v[160:163], v[2:3], off
	global_load_dwordx4 v[164:167], v[2:3], off offset:32
	global_load_dwordx4 v[168:171], v[2:3], off offset:16
	global_load_dwordx4 v[172:175], v[2:3], off offset:48
	v_lshl_add_u32 v226, v4, 10, v1
.LBB0_1684:
	s_or_b64 exec, exec, s[10:11]
	v_add_u32_e32 v5, 2, v4
	v_mov_b64_e32 v[2:3], s[2:3]
	v_mad_i64_i32 v[2:3], s[10:11], v5, s24, v[2:3]
	s_mov_b64 s[10:11], 0x5c2
	s_nop 0
	v_cmp_gt_i64_e32 vcc, s[10:11], v[2:3]
	s_and_saveexec_b64 s[10:11], vcc
	s_cbranch_execz .LBB0_1690
	v_ashrrev_i32_e32 v3, 31, v2
	v_lshrrev_b32_e32 v3, 29, v3
	v_add_u32_e32 v6, v2, v3
	v_and_b32_e32 v3, -8, v6
	v_sub_u32_e32 v3, v2, v3
	v_cmp_lt_i32_e32 vcc, 1, v3
	s_and_saveexec_b64 s[12:13], vcc
	s_xor_b64 s[12:13], exec, s[12:13]
	s_movk_i32 s18, 0xb8
	v_mul_lo_u32 v2, v3, s18
	v_or_b32_e32 v2, 2, v2
	s_or_saveexec_b64 s[12:13], s[12:13]
	v_ashrrev_i32_e32 v6, 3, v6
	s_xor_b64 exec, exec, s[12:13]
	s_movk_i32 s18, 0xb9
	v_mul_lo_u32 v2, v3, s18
	s_or_b64 exec, exec, s[12:13]
	v_add_u32_e32 v2, v2, v6
	s_mov_b32 s12, 0x2e8ba2e9
	v_mul_hi_i32 v3, v2, s12
	v_lshrrev_b32_e32 v6, 31, v3
	v_ashrrev_i32_e32 v3, 5, v3
	v_add_u32_e32 v3, v3, v6
	v_lshlrev_b32_e32 v6, 3, v3
	v_sub_u32_e32 v7, 0x43, v6
	v_min_i32_e32 v7, 8, v7
	v_sub_u32_e32 v8, 0, v7
	v_max_i32_e32 v7, v7, v8
	v_cvt_f32_u32_e32 v8, v7
	s_movk_i32 s12, 0xb0
	v_mul_lo_u32 v3, v3, s12
	v_sub_u32_e32 v2, v2, v3
	v_rcp_iflag_f32_e32 v8, v8
	v_sub_u32_e32 v9, 0, v2
	v_ashrrev_i32_e32 v3, 31, v2
	v_max_i32_e32 v2, v2, v9
	v_mul_f32_e32 v8, 0x4f7ffffe, v8
	v_cvt_u32_f32_e32 v8, v8
	v_sub_u32_e32 v9, 0, v7
	s_movk_i32 s12, 0xf8
	v_mul_lo_u32 v9, v9, v8
	v_mul_hi_u32 v9, v8, v9
	v_add_u32_e32 v8, v8, v9
	v_mul_hi_u32 v8, v2, v8
	v_mul_lo_u32 v8, v8, v7
	v_sub_u32_e32 v2, v2, v8
	v_sub_u32_e32 v8, v2, v7
	v_cmp_ge_u32_e32 vcc, v2, v7
	s_nop 1
	v_cndmask_b32_e32 v2, v2, v8, vcc
	v_sub_u32_e32 v8, v2, v7
	v_cmp_ge_u32_e32 vcc, v2, v7
	s_nop 1
	v_cndmask_b32_e32 v2, v2, v8, vcc
	v_xor_b32_e32 v2, v2, v3
	v_sub_u32_e32 v2, v2, v3
	v_add_u32_e32 v2, v6, v2
	v_mad_u64_u32 v[2:3], s[12:13], v2, s12, v[0:1]
	v_mov_b32_e32 v3, 0x4001
	v_med3_i32 v2, v2, 2, v3
	v_add_u32_e32 v2, -2, v2
	v_mov_b32_e32 v3, 0
	v_lshlrev_b64 v[2:3], 6, v[2:3]
	s_waitcnt lgkmcnt(0)
	v_lshl_add_u64 v[2:3], s[16:17], 0, v[2:3]
	s_mov_b64 s[86:87], exec
	global_load_dwordx4 v[176:179], v[2:3], off
	global_load_dwordx4 v[180:183], v[2:3], off offset:32
	global_load_dwordx4 v[184:187], v[2:3], off offset:16
	global_load_dwordx4 v[188:191], v[2:3], off offset:48
	v_lshl_add_u32 v227, v5, 10, v1
.LBB0_1690:
	s_or_b64 exec, exec, s[10:11]
	v_add_u32_e32 v5, 4, v4
	v_mov_b64_e32 v[2:3], s[2:3]
	v_mad_i64_i32 v[2:3], s[10:11], v5, s24, v[2:3]
	s_mov_b64 s[10:11], 0x5c2
	s_nop 0
	v_cmp_gt_i64_e32 vcc, s[10:11], v[2:3]
	s_and_saveexec_b64 s[10:11], vcc
	s_cbranch_execz .LBB0_1696
	v_ashrrev_i32_e32 v3, 31, v2
	v_lshrrev_b32_e32 v3, 29, v3
	v_add_u32_e32 v6, v2, v3
	v_and_b32_e32 v3, -8, v6
	v_sub_u32_e32 v3, v2, v3
	v_cmp_lt_i32_e32 vcc, 1, v3
	s_and_saveexec_b64 s[12:13], vcc
	s_xor_b64 s[12:13], exec, s[12:13]
	s_movk_i32 s18, 0xb8
	v_mul_lo_u32 v2, v3, s18
	v_or_b32_e32 v2, 2, v2
	s_or_saveexec_b64 s[12:13], s[12:13]
	v_ashrrev_i32_e32 v6, 3, v6
	s_xor_b64 exec, exec, s[12:13]
	s_movk_i32 s18, 0xb9
	v_mul_lo_u32 v2, v3, s18
	s_or_b64 exec, exec, s[12:13]
	v_add_u32_e32 v2, v2, v6
	s_mov_b32 s12, 0x2e8ba2e9
	v_mul_hi_i32 v3, v2, s12
	v_lshrrev_b32_e32 v6, 31, v3
	v_ashrrev_i32_e32 v3, 5, v3
	v_add_u32_e32 v3, v3, v6
	v_lshlrev_b32_e32 v6, 3, v3
	v_sub_u32_e32 v7, 0x43, v6
	v_min_i32_e32 v7, 8, v7
	v_sub_u32_e32 v8, 0, v7
	v_max_i32_e32 v7, v7, v8
	v_cvt_f32_u32_e32 v8, v7
	s_movk_i32 s12, 0xb0
	v_mul_lo_u32 v3, v3, s12
	v_sub_u32_e32 v2, v2, v3
	v_rcp_iflag_f32_e32 v8, v8
	v_sub_u32_e32 v9, 0, v2
	v_ashrrev_i32_e32 v3, 31, v2
	v_max_i32_e32 v2, v2, v9
	v_mul_f32_e32 v8, 0x4f7ffffe, v8
	v_cvt_u32_f32_e32 v8, v8
	v_sub_u32_e32 v9, 0, v7
	s_movk_i32 s12, 0xf8
	v_mul_lo_u32 v9, v9, v8
	v_mul_hi_u32 v9, v8, v9
	v_add_u32_e32 v8, v8, v9
	v_mul_hi_u32 v8, v2, v8
	v_mul_lo_u32 v8, v8, v7
	v_sub_u32_e32 v2, v2, v8
	v_sub_u32_e32 v8, v2, v7
	v_cmp_ge_u32_e32 vcc, v2, v7
	s_nop 1
	v_cndmask_b32_e32 v2, v2, v8, vcc
	v_sub_u32_e32 v8, v2, v7
	v_cmp_ge_u32_e32 vcc, v2, v7
	s_nop 1
	v_cndmask_b32_e32 v2, v2, v8, vcc
	v_xor_b32_e32 v2, v2, v3
	v_sub_u32_e32 v2, v2, v3
	v_add_u32_e32 v2, v6, v2
	v_mad_u64_u32 v[2:3], s[12:13], v2, s12, v[0:1]
	v_mov_b32_e32 v3, 0x4001
	v_med3_i32 v2, v2, 2, v3
	v_add_u32_e32 v2, -2, v2
	v_mov_b32_e32 v3, 0
	v_lshlrev_b64 v[2:3], 6, v[2:3]
	s_waitcnt lgkmcnt(0)
	v_lshl_add_u64 v[2:3], s[16:17], 0, v[2:3]
	s_mov_b64 s[88:89], exec
	global_load_dwordx4 v[192:195], v[2:3], off
	global_load_dwordx4 v[196:199], v[2:3], off offset:32
	global_load_dwordx4 v[200:203], v[2:3], off offset:16
	global_load_dwordx4 v[204:207], v[2:3], off offset:48
	v_lshl_add_u32 v228, v5, 10, v1
.LBB0_1696:
	s_or_b64 exec, exec, s[10:11]
	v_add_u32_e32 v4, 6, v4
	v_mov_b64_e32 v[2:3], s[2:3]
	v_mad_i64_i32 v[2:3], s[10:11], v4, s24, v[2:3]
	s_mov_b64 s[10:11], 0x5c2
	s_nop 0
	v_cmp_gt_i64_e32 vcc, s[10:11], v[2:3]
	s_and_saveexec_b64 s[10:11], vcc
	s_cbranch_execz .LBB0_1702
	v_ashrrev_i32_e32 v3, 31, v2
	v_lshrrev_b32_e32 v3, 29, v3
	v_add_u32_e32 v5, v2, v3
	v_and_b32_e32 v3, -8, v5
	v_sub_u32_e32 v3, v2, v3
	v_cmp_lt_i32_e32 vcc, 1, v3
	s_and_saveexec_b64 s[12:13], vcc
	s_xor_b64 s[12:13], exec, s[12:13]
	s_movk_i32 s18, 0xb8
	v_mul_lo_u32 v2, v3, s18
	v_or_b32_e32 v2, 2, v2
	s_or_saveexec_b64 s[12:13], s[12:13]
	v_ashrrev_i32_e32 v5, 3, v5
	s_xor_b64 exec, exec, s[12:13]
	s_movk_i32 s18, 0xb9
	v_mul_lo_u32 v2, v3, s18
	s_or_b64 exec, exec, s[12:13]
	v_add_u32_e32 v2, v2, v5
	s_mov_b32 s12, 0x2e8ba2e9
	v_mul_hi_i32 v3, v2, s12
	v_lshrrev_b32_e32 v5, 31, v3
	v_ashrrev_i32_e32 v3, 5, v3
	v_add_u32_e32 v3, v3, v5
	v_lshlrev_b32_e32 v5, 3, v3
	v_sub_u32_e32 v6, 0x43, v5
	v_min_i32_e32 v6, 8, v6
	v_sub_u32_e32 v7, 0, v6
	v_max_i32_e32 v6, v6, v7
	v_cvt_f32_u32_e32 v7, v6
	s_movk_i32 s12, 0xb0
	v_mul_lo_u32 v3, v3, s12
	v_sub_u32_e32 v2, v2, v3
	v_rcp_iflag_f32_e32 v7, v7
	v_sub_u32_e32 v8, 0, v2
	v_ashrrev_i32_e32 v3, 31, v2
	v_max_i32_e32 v2, v2, v8
	v_mul_f32_e32 v7, 0x4f7ffffe, v7
	v_cvt_u32_f32_e32 v7, v7
	v_sub_u32_e32 v8, 0, v6
	s_movk_i32 s12, 0xf8
	v_mul_lo_u32 v8, v8, v7
	v_mul_hi_u32 v8, v7, v8
	v_add_u32_e32 v7, v7, v8
	v_mul_hi_u32 v7, v2, v7
	v_mul_lo_u32 v7, v7, v6
	v_sub_u32_e32 v2, v2, v7
	v_sub_u32_e32 v7, v2, v6
	v_cmp_ge_u32_e32 vcc, v2, v6
	s_nop 1
	v_cndmask_b32_e32 v2, v2, v7, vcc
	v_sub_u32_e32 v7, v2, v6
	v_cmp_ge_u32_e32 vcc, v2, v6
	s_nop 1
	v_cndmask_b32_e32 v2, v2, v7, vcc
	v_xor_b32_e32 v2, v2, v3
	v_sub_u32_e32 v2, v2, v3
	v_add_u32_e32 v2, v5, v2
	v_mad_u64_u32 v[2:3], s[12:13], v2, s12, v[0:1]
	v_mov_b32_e32 v0, 0x4001
	v_med3_i32 v0, v2, 2, v0
	v_add_u32_e32 v2, -2, v0
	v_mov_b32_e32 v3, 0
	v_lshlrev_b64 v[2:3], 6, v[2:3]
	s_waitcnt lgkmcnt(0)
	v_lshl_add_u64 v[2:3], s[16:17], 0, v[2:3]
	s_mov_b64 s[90:91], exec
	global_load_dwordx4 v[208:211], v[2:3], off
	global_load_dwordx4 v[212:215], v[2:3], off offset:32
	global_load_dwordx4 v[216:219], v[2:3], off offset:16
	global_load_dwordx4 v[220:223], v[2:3], off offset:48
	v_lshl_add_u32 v229, v4, 10, v1
.LBB0_1702:
	s_or_b64 exec, exec, s[10:11]
	s_mov_b64 s[92:93], exec
	s_waitcnt vmcnt(0)
	s_mov_b64 exec, s[84:85]
	s_cbranch_execz .Lfr_49081_0
	v_mov_b32_e32 v2, v160
	v_mov_b32_e32 v3, v164
	v_mov_b32_e32 v164, v161
	v_mov_b32_e32 v160, v162
	v_mov_b32_e32 v161, v166
	v_mov_b32_e32 v166, v163
	v_mov_b32_e32 v162, v168
	v_mov_b32_e32 v163, v172
	v_mov_b32_e32 v172, v169
	v_mov_b32_e32 v168, v170
	v_mov_b32_e32 v169, v174
	v_mov_b32_e32 v174, v171
	v_pk_add_f32 v[2:3], v[2:3], v[164:165]
	v_pk_add_f32 v[160:161], v[160:161], v[166:167]
	v_pk_add_f32 v[162:163], v[162:163], v[172:173]
	v_pk_add_f32 v[164:165], v[168:169], v[174:175]
	v_pk_add_f32 v[2:3], v[2:3], v[160:161]
	v_pk_add_f32 v[160:161], v[162:163], v[164:165]
	s_nop 0
	v_pk_add_f32 v[2:3], v[2:3], v[160:161]
	s_nop 0
	v_add_f32_e32 v2, v2, v3
	v_mov_b32_e32 v3, 0x358637bd
	v_fmac_f32_e32 v3, 0x3a800000, v2
	v_rsq_f32_e32 v2, v3
	ds_write_b32 v226, v2

.Lfr_49081_3:
	s_mov_b64 exec, s[92:93]
	v_mov_b32_e32 v8, v224
	s_waitcnt lgkmcnt(0)
	s_barrier
	s_and_b64 vcc, exec, s[34:35]
	v_readfirstlane_b32 s27, v8
	s_cbranch_vccz .LBB0_1704
	s_or_b32 s10, s97, 2
	s_cmp_lt_i32 s75, 2
	s_cselect_b32 s10, s80, s10
	s_add_i32 s10, s10, s72
	s_mul_hi_i32 s11, s10, 0x2e8ba2e9
	s_lshr_b32 s12, s11, 31
	s_ashr_i32 s11, s11, 5
	s_add_i32 s11, s11, s12
	s_lshl_b32 s13, s11, 3
	s_sub_i32 s12, 0x43, s13
	s_min_i32 s18, s12, 8
	s_abs_i32 s12, s18
	v_cvt_f32_u32_e32 v0, s12
	s_sub_i32 s20, 0, s12
	s_mulk_i32 s11, 0xb0
	s_sub_i32 s10, s10, s11
	v_rcp_iflag_f32_e32 v0, v0
	s_abs_i32 s11, s10
	s_xor_b32 s19, s10, s18
	s_ashr_i32 s19, s19, 31
	v_mul_f32_e32 v0, 0x4f7ffffe, v0
	v_cvt_u32_f32_e32 v0, v0
	s_nop 0
	v_readfirstlane_b32 s21, v0
	s_mul_i32 s20, s20, s21
	s_mul_hi_u32 s20, s21, s20
	s_add_i32 s21, s21, s20
	s_mul_hi_u32 s20, s11, s21
	s_mul_i32 s21, s20, s12
	s_sub_i32 s11, s11, s21
	s_add_i32 s22, s20, 1
	s_sub_i32 s21, s11, s12
	s_cmp_ge_u32 s11, s12
	s_cselect_b32 s20, s22, s20
	s_cselect_b32 s11, s21, s11
	s_add_i32 s21, s20, 1
	s_cmp_ge_u32 s11, s12
	s_cselect_b32 s11, s21, s20
	s_xor_b32 s11, s11, s19
	s_sub_i32 s12, s11, s19
	s_mul_i32 s11, s12, s18
	s_sub_i32 s10, s10, s11
	s_add_i32 s26, s10, s13
